# sample FOX cache stream loads use system-scope (sc0 sc1 nt) cache policy to bypass the per-CU L1 miss path
# speedup vs baseline: 1.0127x; 1.0127x over previous
; #define LDS_AS __attribute__((address_space(3)))
;     ...
;     const float* ck = (MODE == 0 ? p.cak : p.cbk) + (size_t)bb * PAST * 512;
;     const float* cv = (MODE == 0 ? p.cav : p.cbv) + (size_t)bb * PAST * 512;
;     const int ntc = (MODE == 1 ? (PAST / NSPLIT / 32) : 128), kbase = (MODE == 1 ? (PAST / NSPLIT) * split : 0);
;     const bool has_new = (MODE == 0) || (split == NSPLIT - 1);
;     const float* cseq = p.c2s + (size_t)(bb * 8 + ((tid >> 5) & 7)) * LSK;
;     float cref = 0.f;
;     if (MODE == 1 && tid < 256) cref = cseq[PAST];
;     constexpr int KOFF = 0, VOFF = 36864, BOFF = 73728, HSTR = 4608;
;     bool wdone = false, alldone = false;
;     if (has_new) {
;         __syncthreads();
;         const bf16_t* kb = p.u + ((size_t)ROWS_P + bb * 32) * NU + segb + 512;
; #pragma unroll
;         for (int i = 0; i < 4; ++i) {
;             const int id = tid + 512 * i, r = id >> 6, c = id & 63, hd = c >> 3, d = (c & 7) * 8;
;             const u32x4 kx = *(const u32x4*)(kb + (size_t)r * NU + c * 8);
;             const u32x4 vx = *(const u32x4*)(kb + (size_t)r * NU + 512 + c * 8);
;             *(LDS_AS u32x4*)(lb + KOFF + hd * HSTR + r * 144 + d * 2) = kx;
;             *(LDS_AS u32x4*)(lb + VOFF + hd * HSTR + r * 144 + d * 2) = vx;
;         }
;         if (MODE == 1 && tid < 256) *(LDS_AS float*)(lb + BOFF + tid * 4) = cref - cseq[PAST + (tid & 31)];
;         __syncthreads();
;         attn_subtile<MODE>(lb + KOFF + wave * HSTR, lb + VOFF + wave * HSTR, lb + BOFF + wave * 128, q, st, PAST, qpos, true, lane);
;         if (MODE == 0) { wdone = __all(st.l < -SB_THRESH); alldone = __syncthreads_and(wdone ? 1 : 0) != 0; }
;     }
;     if (!alldone) {
;         f32x4 tk[8], tv[8]; float tb = 0.f;
;         const int rot = (MODE == 1) ? ((bb * NSPLIT + split) * 5) % ntc : 0;
;         {
;             const int t0i = (ntc - 1 + rot) % ntc;
;             const float* kg = ck + (size_t)(kbase + 32 * t0i) * 512;
;             const float* vg = cv + (size_t)(kbase + 32 * t0i) * 512;
;             if (MODE == 1 && tid < 256) tb = cseq[kbase + 32 * t0i + (tid & 31)];
; #pragma unroll
;             for (int i = 0; i < 8; ++i) { const int id = tid + 512 * i; tk[i] = __builtin_nontemporal_load((const f32x4*)(kg + (size_t)id * 4)); tv[i] = __builtin_nontemporal_load((const f32x4*)(vg + (size_t)id * 4)); }
;         }
.LBB0_455:
	s_or_b64 exec, exec, s[34:35]
	s_ashr_i32 s7, s6, 31
	s_lshl_b64 s[34:35], s[6:7], 23
	s_add_u32 s36, s84, s34
	s_addc_u32 s37, s85, s35
	s_add_u32 s38, s86, s34
	s_addc_u32 s39, s87, s35
	s_ashr_i32 s31, s30, 31
	s_lshl_b64 s[30:31], s[30:31], 11
	s_add_u32 s34, s36, s30
	s_addc_u32 s35, s37, s31
	s_add_u32 s30, s38, s30
	v_ashrrev_i32_e32 v135, 31, v134
	s_addc_u32 s31, s39, s31
	v_lshlrev_b64 v[40:41], 4, v[134:135]
	v_lshl_add_u64 v[42:43], s[34:35], 0, v[40:41]
	v_lshl_add_u64 v[40:41], s[30:31], 0, v[40:41]
	v_ashrrev_i32_e32 v37, 31, v36
	global_load_dwordx4 v[68:71], v[40:41], off sc0 sc1 nt
	v_lshlrev_b64 v[40:41], 4, v[36:37]
	global_load_dwordx4 v[64:67], v[42:43], off sc0 sc1 nt
	v_lshl_add_u64 v[42:43], s[34:35], 0, v[40:41]
	v_lshl_add_u64 v[40:41], s[30:31], 0, v[40:41]
	v_ashrrev_i32_e32 v35, 31, v34
	global_load_dwordx4 v[76:79], v[40:41], off sc0 sc1 nt
	v_lshlrev_b64 v[40:41], 4, v[34:35]
	global_load_dwordx4 v[72:75], v[42:43], off sc0 sc1 nt
	v_lshl_add_u64 v[42:43], s[34:35], 0, v[40:41]
	v_lshl_add_u64 v[40:41], s[30:31], 0, v[40:41]
	v_ashrrev_i32_e32 v33, 31, v32
	global_load_dwordx4 v[84:87], v[40:41], off sc0 sc1 nt
	v_lshlrev_b64 v[40:41], 4, v[32:33]
	global_load_dwordx4 v[80:83], v[42:43], off sc0 sc1 nt
	v_lshl_add_u64 v[42:43], s[34:35], 0, v[40:41]
	v_lshl_add_u64 v[40:41], s[30:31], 0, v[40:41]
	global_load_dwordx4 v[92:95], v[40:41], off sc0 sc1 nt
	v_add_u32_e32 v40, 0x800, v134
	v_ashrrev_i32_e32 v41, 31, v40
	global_load_dwordx4 v[88:91], v[42:43], off sc0 sc1 nt
	v_lshlrev_b64 v[42:43], 4, v[40:41]
	v_lshl_add_u64 v[44:45], s[34:35], 0, v[42:43]
	v_lshl_add_u64 v[42:43], s[30:31], 0, v[42:43]
	global_load_dwordx4 v[100:103], v[42:43], off sc0 sc1 nt
	v_add_u32_e32 v42, 0xa00, v134
	v_ashrrev_i32_e32 v43, 31, v42
	global_load_dwordx4 v[96:99], v[44:45], off sc0 sc1 nt
	v_lshlrev_b64 v[44:45], 4, v[42:43]
	v_lshl_add_u64 v[46:47], s[34:35], 0, v[44:45]
	v_lshl_add_u64 v[44:45], s[30:31], 0, v[44:45]
	global_load_dwordx4 v[108:111], v[44:45], off sc0 sc1 nt
	v_add_u32_e32 v44, 0xc00, v134
	v_ashrrev_i32_e32 v45, 31, v44
	global_load_dwordx4 v[104:107], v[46:47], off sc0 sc1 nt
	v_lshlrev_b64 v[46:47], 4, v[44:45]
	s_waitcnt vmcnt(27)
	v_lshl_add_u64 v[112:113], s[34:35], 0, v[46:47]
	v_lshl_add_u64 v[46:47], s[30:31], 0, v[46:47]
	global_load_dwordx4 v[116:119], v[46:47], off sc0 sc1 nt
	v_add_u32_e32 v46, 0xe00, v134
	v_ashrrev_i32_e32 v47, 31, v46
	s_waitcnt vmcnt(25)
	v_lshlrev_b64 v[124:125], 4, v[46:47]
	v_lshl_add_u64 v[120:121], s[34:35], 0, v[124:125]
	v_lshl_add_u64 v[124:125], s[30:31], 0, v[124:125]
	global_load_dwordx4 v[112:115], v[112:113], off sc0 sc1 nt
	v_lshlrev_b64 v[160:161], 2, v[42:43]
	global_load_dwordx4 v[120:123], v[120:121], off sc0 sc1 nt
	v_and_b32_e32 v43, 64, v174
	global_load_dwordx4 v[124:127], v[124:125], off sc0 sc1 nt
	v_lshlrev_b64 v[158:159], 2, v[40:41]
	v_xor_b32_e32 v41, 32, v174
	v_add_u32_e32 v43, 64, v43
	v_cmp_lt_i32_e32 vcc, v41, v43
	v_lshlrev_b64 v[154:155], 2, v[34:35]
	v_lshlrev_b64 v[156:157], 2, v[32:33]
	v_bfe_u32 v33, v134, 4, 3
	v_lshlrev_b32_e32 v35, 3, v134
	v_cndmask_b32_e32 v41, v174, v41, vcc
	v_lshlrev_b64 v[150:151], 2, v[134:135]
	v_and_b32_e32 v35, 0x78, v35
	v_mul_u32_u24_e32 v33, 0x1200, v33
	v_lshlrev_b32_e32 v181, 2, v41
	v_lshrrev_b32_e32 v41, 2, v134
	v_lshlrev_b32_e32 v135, 2, v38
	v_add3_u32 v33, s62, v33, v35
	v_mul_lo_u32 v35, v136, s91
	v_and_b32_e32 v43, 16, v134
	v_and_or_b32 v38, v41, 3, v135
	v_lshlrev_b32_e32 v41, 2, v133
	v_add_u32_e32 v35, 0x100, v35
	v_and_or_b32 v41, v41, 12, v43
	v_ashrrev_i32_e32 v32, 7, v32
	v_lshlrev_b64 v[152:153], 2, v[36:37]
	v_lshlrev_b64 v[162:163], 2, v[44:45]
	s_add_i32 s30, s92, 0x100
	v_mad_u32_u24 v39, v176, s89, v35
	v_mad_u32_u24 v35, v38, s89, v35
	v_lshlrev_b32_e32 v38, 1, v41
	v_lshlrev_b32_e32 v41, 2, v134
	v_ashrrev_i32_e32 v43, 7, v134
	v_ashrrev_i32_e32 v36, 7, v36
	v_ashrrev_i32_e32 v34, 7, v34
	v_mul_lo_u32 v32, v32, s89
	v_ashrrev_i32_e32 v40, 7, v40
	v_ashrrev_i32_e32 v42, 7, v42
	v_ashrrev_i32_e32 v44, 7, v44
	v_ashrrev_i32_e32 v45, 7, v46
	v_lshlrev_b64 v[164:165], 2, v[46:47]
	v_lshl_add_u32 v37, v136, 7, s30
	v_mul_lo_u32 v43, v43, s89
	v_mul_lo_u32 v36, v36, s89
	v_mul_lo_u32 v34, v34, s89
	v_mul_lo_u32 v40, v40, s89
	v_mul_lo_u32 v42, v42, s89
	v_mul_lo_u32 v44, v44, s89
	v_mul_lo_u32 v45, v45, s89
	v_add_u32_e32 v185, v33, v32
	v_add_u32_e32 v32, 0x100, v41
	s_movk_i32 s42, 0x7c0
	v_add_u32_e32 v182, v33, v43
	v_add_u32_e32 v183, v33, v36
	v_add_u32_e32 v184, v33, v34
	v_add_u32_e32 v186, v33, v40
	v_add_u32_e32 v187, v33, v42
	v_add_u32_e32 v188, v33, v44
	v_add_u32_e32 v189, v33, v45
	v_add_u32_e32 v190, 0x12000, v32
	v_lshlrev_b64 v[150:151], 2, v[150:151]
	v_lshlrev_b64 v[152:153], 2, v[152:153]
	v_lshlrev_b64 v[154:155], 2, v[154:155]
	v_lshlrev_b64 v[156:157], 2, v[156:157]
	v_lshlrev_b64 v[158:159], 2, v[158:159]
	v_lshlrev_b64 v[160:161], 2, v[160:161]
	v_lshlrev_b64 v[162:163], 2, v[162:163]
	v_lshlrev_b64 v[164:165], 2, v[164:165]
	v_add_u32_e32 v191, v37, v130
	v_add_u32_e32 v130, v39, v130
	v_add_u32_e32 v192, v35, v38
	v_lshrrev_b32_e32 v32, 4, v174
	v_and_b32_e32 v33, 15, v174
	v_lshlrev_b32_e32 v34, 11, v32
	v_lshl_add_u32 v34, v136, 8, v34
	v_lshl_add_u32 v34, v33, 4, v34
	v_mov_b32_e32 v150, v34
	v_mov_b32_e32 v151, 0
	v_add_u32_e32 v152, 0x2000, v34
	v_mov_b32_e32 v153, 0
	v_add_u32_e32 v154, 0x4000, v34
	v_mov_b32_e32 v155, 0
	v_add_u32_e32 v156, 0x6000, v34
	v_mov_b32_e32 v157, 0
	v_add_u32_e32 v158, 0x8000, v34
	v_mov_b32_e32 v159, 0
	v_add_u32_e32 v160, 0xa000, v34
	v_mov_b32_e32 v161, 0
	v_add_u32_e32 v162, 0xc000, v34
	v_mov_b32_e32 v163, 0
	v_add_u32_e32 v164, 0xe000, v34
	v_mov_b32_e32 v165, 0
	v_mul_u32_u24_e32 v35, 0x1200, v136
	v_mad_u32_u24 v35, v32, s89, v35
	v_lshl_add_u32 v35, v33, 3, v35
	v_add_u32_e32 v35, 0x100, v35
	v_mov_b32_e32 v182, v35
	v_add_u32_e32 v183, 0x240, v35
	v_add_u32_e32 v184, 0x480, v35
	v_add_u32_e32 v185, 0x6c0, v35
	v_add_u32_e32 v186, 0x900, v35
	v_add_u32_e32 v187, 0xb40, v35
	v_add_u32_e32 v188, 0xd80, v35
	v_add_u32_e32 v189, 0xfc0, v35
	v_cmp_gt_u32_e64 s[0:1], 32, v174
	v_lshl_add_u32 v36, s6, 3, v136
	v_mul_u32_u24_e32 v36, 0x4080, v36
	v_mov_b32_e32 v37, 0
	v_lshl_add_u64 v[148:149], s[74:75], 0, v[36:37]
	v_lshlrev_b32_e32 v190, 2, v176
	v_lshl_add_u32 v190, v136, 7, v190
	v_add_u32_e32 v190, 0x12100, v190
	v_mov_b32_e32 v36, 0x4000
	v_lshl_add_u64 v[36:37], v[148:149], 0, v[36:37]
	global_load_dword v177, v[36:37], off
	s_add_i32 s30, s10, s42
	s_add_i32 s30, s30, 32
	s_and_b32 s30, s30, 0x3e0
	s_or_b32 s30, s30, s9
	s_and_saveexec_b64 s[34:35], s[0:1]
	s_cbranch_execz .Lss_z461
	v_or_b32_e32 v32, s30, v176
	v_ashrrev_i32_e32 v33, 31, v32
	v_lshl_add_u64 v[32:33], v[32:33], 2, v[148:149]
	global_load_dword v179, v[32:33], off
; #define LDS_AS __attribute__((address_space(3)))
; DI unsigned pk2(float a, float b) { f32x2 v = {a, b}; bf16x2v r = __builtin_convertvector(v, bf16x2v); return __builtin_bit_cast(unsigned, r); }
;     ...
;         f32x4 tk[8], tv[8]; float tb = 0.f;
;         const int rot = (MODE == 1) ? ((bb * NSPLIT + split) * 5) % ntc : 0;
;         {
;             const int t0i = (ntc - 1 + rot) % ntc;
;             const float* kg = ck + (size_t)(kbase + 32 * t0i) * 512;
;             const float* vg = cv + (size_t)(kbase + 32 * t0i) * 512;
;             if (MODE == 1 && tid < 256) tb = cseq[kbase + 32 * t0i + (tid & 31)];
; #pragma unroll
;             for (int i = 0; i < 8; ++i) { const int id = tid + 512 * i; tk[i] = __builtin_nontemporal_load((const f32x4*)(kg + (size_t)id * 4)); tv[i] = __builtin_nontemporal_load((const f32x4*)(vg + (size_t)id * 4)); }
;         }
;     ...
;             const int kpos0 = kbase + 32 * ((it + rot) % ntc);
;             const int kposn = kbase + 32 * ((it - 1 + rot + ntc) % ntc);
;             __syncthreads();
; #pragma unroll
;             for (int i = 0; i < 8; ++i) {
;                 const int id = tid + 512 * i, r = id >> 7, c4 = id & 127, hd = c4 >> 4, d = (c4 & 15) * 4;
;                 *(LDS_AS u32x2*)(lb + KOFF + hd * HSTR + r * 144 + d * 2) = (u32x2){pk2(tk[i][0], tk[i][1]), pk2(tk[i][2], tk[i][3])};
;                 *(LDS_AS u32x2*)(lb + VOFF + hd * HSTR + r * 144 + d * 2) = (u32x2){pk2(tv[i][0], tv[i][1]), pk2(tv[i][2], tv[i][3])};
;             }
;             if (MODE == 1 && tid < 256) *(LDS_AS float*)(lb + BOFF + tid * 4) = cref - tb;
;             if (it > 0) {
;                 const float* kg = ck + (size_t)kposn * 512;
;                 const float* vg = cv + (size_t)kposn * 512;
;                 if (MODE == 1 && tid < 256) tb = cseq[kposn + (tid & 31)];
; #pragma unroll
;                 for (int i = 0; i < 8; ++i) { const int id = tid + 512 * i; tk[i] = __builtin_nontemporal_load((const f32x4*)(kg + (size_t)id * 4)); tv[i] = __builtin_nontemporal_load((const f32x4*)(vg + (size_t)id * 4)); }
.Lss_z461:
	s_or_b64 exec, exec, s[34:35]
	s_ashr_i32 s31, s30, 31
	s_lshl_b64 s[30:31], s[30:31], 11
	s_add_u32 s34, s36, s30
	s_addc_u32 s35, s37, s31
	s_add_u32 s30, s38, s30
	s_addc_u32 s31, s39, s31
	v_lshl_add_u64 v[32:33], s[34:35], 0, v[150:151]
	global_load_dwordx4 v[64:67], v[32:33], off sc0 sc1 nt
	v_lshl_add_u64 v[32:33], s[30:31], 0, v[150:151]
	global_load_dwordx4 v[68:71], v[32:33], off sc0 sc1 nt
	v_lshl_add_u64 v[32:33], s[34:35], 0, v[152:153]
	global_load_dwordx4 v[72:75], v[32:33], off sc0 sc1 nt
	v_lshl_add_u64 v[32:33], s[30:31], 0, v[152:153]
	global_load_dwordx4 v[76:79], v[32:33], off sc0 sc1 nt
	v_lshl_add_u64 v[32:33], s[34:35], 0, v[154:155]
	global_load_dwordx4 v[80:83], v[32:33], off sc0 sc1 nt
	v_lshl_add_u64 v[32:33], s[30:31], 0, v[154:155]
	global_load_dwordx4 v[84:87], v[32:33], off sc0 sc1 nt
	v_lshl_add_u64 v[32:33], s[34:35], 0, v[156:157]
	global_load_dwordx4 v[88:91], v[32:33], off sc0 sc1 nt
	v_lshl_add_u64 v[32:33], s[30:31], 0, v[156:157]
	global_load_dwordx4 v[92:95], v[32:33], off sc0 sc1 nt
	v_lshl_add_u64 v[32:33], s[34:35], 0, v[158:159]
	global_load_dwordx4 v[96:99], v[32:33], off sc0 sc1 nt
	v_lshl_add_u64 v[32:33], s[30:31], 0, v[158:159]
	global_load_dwordx4 v[100:103], v[32:33], off sc0 sc1 nt
	v_lshl_add_u64 v[32:33], s[34:35], 0, v[160:161]
	global_load_dwordx4 v[104:107], v[32:33], off sc0 sc1 nt
	v_lshl_add_u64 v[32:33], s[30:31], 0, v[160:161]
	global_load_dwordx4 v[108:111], v[32:33], off sc0 sc1 nt
	v_lshl_add_u64 v[32:33], s[34:35], 0, v[162:163]
	global_load_dwordx4 v[112:115], v[32:33], off sc0 sc1 nt
	v_lshl_add_u64 v[32:33], s[30:31], 0, v[162:163]
	global_load_dwordx4 v[116:119], v[32:33], off sc0 sc1 nt
	v_lshl_add_u64 v[32:33], s[34:35], 0, v[164:165]
	global_load_dwordx4 v[120:123], v[32:33], off sc0 sc1 nt
	v_lshl_add_u64 v[32:33], s[30:31], 0, v[164:165]
	global_load_dwordx4 v[124:127], v[32:33], off sc0 sc1 nt
	s_add_i32 s30, s10, s42
	s_and_b32 s30, s30, 0x3e0
	s_or_b32 s30, s30, s9
	s_and_saveexec_b64 s[34:35], s[0:1]
	s_cbranch_execz .Lss_p461
	v_or_b32_e32 v32, s30, v176
	v_ashrrev_i32_e32 v33, 31, v32
	v_lshl_add_u64 v[32:33], v[32:33], 2, v[148:149]
	global_load_dword v144, v[32:33], off
.Lss_p461:
	s_or_b64 exec, exec, s[34:35]
	s_ashr_i32 s31, s30, 31
	s_lshl_b64 s[30:31], s[30:31], 11
	s_add_u32 s34, s36, s30
	s_addc_u32 s35, s37, s31
	s_add_u32 s30, s38, s30
	s_addc_u32 s31, s39, s31
	v_lshl_add_u64 v[32:33], s[34:35], 0, v[150:151]
	global_load_dwordx4 v[204:207], v[32:33], off sc0 sc1 nt
	v_lshl_add_u64 v[32:33], s[30:31], 0, v[150:151]
	global_load_dwordx4 v[208:211], v[32:33], off sc0 sc1 nt
	v_lshl_add_u64 v[32:33], s[34:35], 0, v[152:153]
	global_load_dwordx4 v[212:215], v[32:33], off sc0 sc1 nt
	v_lshl_add_u64 v[32:33], s[30:31], 0, v[152:153]
	global_load_dwordx4 v[216:219], v[32:33], off sc0 sc1 nt
	v_lshl_add_u64 v[32:33], s[34:35], 0, v[154:155]
	global_load_dwordx4 v[220:223], v[32:33], off sc0 sc1 nt
	v_lshl_add_u64 v[32:33], s[30:31], 0, v[154:155]
	global_load_dwordx4 v[224:227], v[32:33], off sc0 sc1 nt
	v_lshl_add_u64 v[32:33], s[34:35], 0, v[156:157]
	global_load_dwordx4 v[228:231], v[32:33], off sc0 sc1 nt
	v_lshl_add_u64 v[32:33], s[30:31], 0, v[156:157]
	global_load_dwordx4 v[232:235], v[32:33], off sc0 sc1 nt
	v_lshl_add_u64 v[32:33], s[34:35], 0, v[158:159]
	global_load_dwordx4 v[236:239], v[32:33], off sc0 sc1 nt
	v_lshl_add_u64 v[32:33], s[30:31], 0, v[158:159]
	global_load_dwordx4 v[240:243], v[32:33], off sc0 sc1 nt
	v_lshl_add_u64 v[32:33], s[34:35], 0, v[160:161]
	global_load_dwordx4 v[244:247], v[32:33], off sc0 sc1 nt
	v_lshl_add_u64 v[32:33], s[30:31], 0, v[160:161]
	global_load_dwordx4 v[248:251], v[32:33], off sc0 sc1 nt
	v_lshl_add_u64 v[32:33], s[34:35], 0, v[162:163]
	global_load_dwordx4 v[252:255], v[32:33], off sc0 sc1 nt
	v_lshl_add_u64 v[32:33], s[30:31], 0, v[162:163]
	global_load_dwordx4 v[140:143], v[32:33], off sc0 sc1 nt
	v_lshl_add_u64 v[32:33], s[34:35], 0, v[164:165]
	global_load_dwordx4 v[166:169], v[32:33], off sc0 sc1 nt
	v_lshl_add_u64 v[32:33], s[30:31], 0, v[164:165]
	global_load_dwordx4 v[170:173], v[32:33], off sc0 sc1 nt

;     ...
;             if (it > 0) {
;                 const float* kg = ck + (size_t)kposn * 512;
;                 const float* vg = cv + (size_t)kposn * 512;
;                 if (MODE == 1 && tid < 256) tb = cseq[kposn + (tid & 31)];
; #pragma unroll
;                 for (int i = 0; i < 8; ++i) { const int id = tid + 512 * i; tk[i] = __builtin_nontemporal_load((const f32x4*)(kg + (size_t)id * 4)); tv[i] = __builtin_nontemporal_load((const f32x4*)(vg + (size_t)id * 4)); }
;             }
.Lss_a461:
	s_or_b64 exec, exec, s[34:35]
	s_ashr_i32 s31, s30, 31
	s_lshl_b64 s[30:31], s[30:31], 11
	s_add_u32 s34, s36, s30
	s_addc_u32 s35, s37, s31
	s_add_u32 s30, s38, s30
	s_addc_u32 s31, s39, s31
	v_lshl_add_u64 v[32:33], s[34:35], 0, v[150:151]
	global_load_dwordx4 v[64:67], v[32:33], off sc0 sc1 nt
	v_lshl_add_u64 v[32:33], s[30:31], 0, v[150:151]
	global_load_dwordx4 v[68:71], v[32:33], off sc0 sc1 nt
	v_lshl_add_u64 v[32:33], s[34:35], 0, v[152:153]
	global_load_dwordx4 v[72:75], v[32:33], off sc0 sc1 nt
	v_lshl_add_u64 v[32:33], s[30:31], 0, v[152:153]
	global_load_dwordx4 v[76:79], v[32:33], off sc0 sc1 nt
	v_lshl_add_u64 v[32:33], s[34:35], 0, v[154:155]
	global_load_dwordx4 v[80:83], v[32:33], off sc0 sc1 nt
	v_lshl_add_u64 v[32:33], s[30:31], 0, v[154:155]
	global_load_dwordx4 v[84:87], v[32:33], off sc0 sc1 nt
	v_lshl_add_u64 v[32:33], s[34:35], 0, v[156:157]
	global_load_dwordx4 v[88:91], v[32:33], off sc0 sc1 nt
	v_lshl_add_u64 v[32:33], s[30:31], 0, v[156:157]
	global_load_dwordx4 v[92:95], v[32:33], off sc0 sc1 nt
	v_lshl_add_u64 v[32:33], s[34:35], 0, v[158:159]
	global_load_dwordx4 v[96:99], v[32:33], off sc0 sc1 nt
	v_lshl_add_u64 v[32:33], s[30:31], 0, v[158:159]
	global_load_dwordx4 v[100:103], v[32:33], off sc0 sc1 nt
	v_lshl_add_u64 v[32:33], s[34:35], 0, v[160:161]
	global_load_dwordx4 v[104:107], v[32:33], off sc0 sc1 nt
	v_lshl_add_u64 v[32:33], s[30:31], 0, v[160:161]
	global_load_dwordx4 v[108:111], v[32:33], off sc0 sc1 nt
	v_lshl_add_u64 v[32:33], s[34:35], 0, v[162:163]
	global_load_dwordx4 v[112:115], v[32:33], off sc0 sc1 nt
	v_lshl_add_u64 v[32:33], s[30:31], 0, v[162:163]
	global_load_dwordx4 v[116:119], v[32:33], off sc0 sc1 nt
	v_lshl_add_u64 v[32:33], s[34:35], 0, v[164:165]
	global_load_dwordx4 v[120:123], v[32:33], off sc0 sc1 nt
	v_lshl_add_u64 v[32:33], s[30:31], 0, v[164:165]
	global_load_dwordx4 v[124:127], v[32:33], off sc0 sc1 nt
